# v71 = v70 + past: lazy softmax reference (running reference max only jumps when exceeded by more than 8 in log2 units; O rescale block skipped wave-uniformly when no row jumped; exact reformulation, f
# baseline (speedup 1.0000x reference)
.LBB0_259:
	ds_read_b128 v[72:75], v116 offset:64
	ds_read_b128 v[100:103], v116 offset:2368
	v_mov_b32_e32 v163, v164
	v_add_u32_e32 v164, s0, v121
	s_waitcnt lgkmcnt(2)
	v_mfma_f32_16x16x32_bf16 v[198:201], v[234:237], v[40:43], 0
	v_mov_b32_e32 v165, v166
	v_add_u32_e32 v166, 0x2000, v164
	v_add_u32_e32 v167, 0x4000, v164
	v_mfma_f32_16x16x32_bf16 v[104:107], v[234:237], v[36:39], 0
	ds_read_b128 v[80:83], v116 offset:4608
	ds_read_b128 v[76:79], v116 offset:4672
	s_addk_i32 s0, 0x80
	s_cmpk_eq_i32 s0, 0x200
	v_mfma_f32_16x16x32_bf16 v[68:71], v[238:241], v[40:43], 0
	v_mfma_f32_16x16x32_bf16 v[64:67], v[238:241], v[36:39], 0
	s_waitcnt lgkmcnt(1)
	v_mfma_f32_16x16x32_bf16 v[92:95], v[80:83], v[40:43], 0
	v_mfma_f32_16x16x32_bf16 v[84:87], v[80:83], v[36:39], 0
	ds_read_b128 v[88:91], v116 offset:6912
	ds_read_b128 v[80:83], v116 offset:6976
	v_add_u32_e32 v116, 0x2400, v116
	s_waitcnt lgkmcnt(1)
	v_mfma_f32_16x16x32_bf16 v[96:99], v[88:91], v[40:43], 0
	v_mfma_f32_16x16x32_bf16 v[88:91], v[88:91], v[36:39], 0
	v_mfma_f32_16x16x32_bf16 v[68:71], v[72:75], v[44:47], v[68:71]
	v_mfma_f32_16x16x32_bf16 v[72:75], v[72:75], v[32:35], v[64:67]
	v_mfma_f32_16x16x32_bf16 v[64:67], v[100:103], v[44:47], v[198:201]
	v_mfma_f32_16x16x32_bf16 v[100:103], v[100:103], v[32:35], v[104:107]
	s_nop 2
	ds_read2_b64 v[104:107], v164 offset1:4
	ds_read2_b64 v[198:201], v164 offset0:8 offset1:12
	v_add_u32_e32 v164, 0x6000, v164
	v_mfma_f32_16x16x32_bf16 v[92:95], v[76:79], v[44:47], v[92:95]
	v_mfma_f32_16x16x32_bf16 v[76:79], v[76:79], v[32:35], v[84:87]
	s_nop 2
	ds_read2_b64 v[84:87], v166 offset0:32 offset1:36
	ds_read2_b64 v[202:205], v166 offset0:40 offset1:44
	ds_read2_b64 v[206:209], v167 offset0:64 offset1:68
	ds_read2_b64 v[210:213], v167 offset0:72 offset1:76
	ds_read2_b64 v[214:217], v164 offset0:96 offset1:100
	ds_read2_b64 v[218:221], v164 offset0:104 offset1:108
	s_waitcnt lgkmcnt(8)
	v_mfma_f32_16x16x32_bf16 v[96:99], v[80:83], v[44:47], v[96:99]
	v_mfma_f32_16x16x32_bf16 v[80:83], v[80:83], v[32:35], v[88:91]
	s_nop 2
	v_max3_f32 v88, v68, s4, v69
	v_max3_f32 v89, v72, s4, v73
	v_max3_f32 v88, v88, v70, v71
	v_max3_f32 v89, v89, v74, v75
	v_max3_f32 v88, v88, v64, v65
	v_max3_f32 v89, v89, v100, v101
	v_max3_f32 v88, v88, v66, v67
	v_max3_f32 v89, v89, v102, v103
	v_max3_f32 v88, v88, v92, v93
	v_max3_f32 v89, v89, v76, v77
	v_max3_f32 v88, v88, v94, v95
	v_max3_f32 v89, v89, v78, v79
	v_max3_f32 v88, v88, v96, v97
	v_max3_f32 v89, v89, v80, v81
	v_max3_f32 v88, v88, v98, v99
	v_max3_f32 v89, v89, v82, v83
	v_mov_b32_e32 v90, v88
	v_mov_b32_e32 v91, v89
	s_nop 0
	v_permlane16_swap_b32_e32 v90, v88
	v_permlane16_swap_b32_e32 v91, v89
	v_max_f32_e32 v88, v88, v90
	v_max_f32_e32 v89, v89, v91
	v_mov_b32_e32 v90, v88
	v_mov_b32_e32 v91, v89
	s_nop 0
	v_permlane32_swap_b32_e32 v90, v88
	v_permlane32_swap_b32_e32 v91, v89
	v_max3_f32 v164, v163, v89, v91
	v_max3_f32 v166, v165, v88, v90
	s_mov_b32 s30, 0x41000000
	v_sub_f32_e32 v89, v164, v163
	v_sub_f32_e32 v88, v166, v165
	v_cmp_lt_f32_e64 s[10:11], s30, v89
	v_cmp_lt_f32_e64 s[12:13], s30, v88
	v_cndmask_b32_e64 v164, v163, v164, s[10:11]
	v_cndmask_b32_e64 v166, v165, v166, s[12:13]
	v_sub_f32_e32 v89, v163, v164
	v_sub_f32_e32 v88, v165, v166
	v_sub_f32_e32 v90, 0, v166
	v_sub_f32_e32 v178, 0, v164
	v_pk_add_f32 v[68:69], v[68:69], v[90:91] op_sel_hi:[1,0]
	v_pk_add_f32 v[70:71], v[70:71], v[90:91] op_sel_hi:[1,0]
	v_pk_add_f32 v[72:73], v[72:73], v[178:179] op_sel_hi:[1,0]
	v_pk_add_f32 v[74:75], v[74:75], v[178:179] op_sel_hi:[1,0]
	v_exp_f32_e32 v88, v88
	v_exp_f32_e32 v89, v89
	v_pk_add_f32 v[64:65], v[64:65], v[90:91] op_sel_hi:[1,0]
	v_pk_add_f32 v[66:67], v[66:67], v[90:91] op_sel_hi:[1,0]
	v_mov_b32_e32 v186, v89
	s_or_b64 s[10:11], s[10:11], s[12:13]
	s_cbranch_scc0 .Lpast_noresc
	v_pk_mul_f32 v[60:61], v[60:61], v[88:89] op_sel_hi:[1,0]
	v_pk_mul_f32 v[62:63], v[62:63], v[88:89] op_sel_hi:[1,0]
	v_pk_mul_f32 v[56:57], v[56:57], v[88:89] op_sel_hi:[1,0]
	v_pk_mul_f32 v[58:59], v[58:59], v[88:89] op_sel_hi:[1,0]
	v_pk_mul_f32 v[52:53], v[52:53], v[88:89] op_sel_hi:[1,0]
	v_pk_mul_f32 v[54:55], v[54:55], v[88:89] op_sel_hi:[1,0]
	v_pk_mul_f32 v[48:49], v[48:49], v[88:89] op_sel_hi:[1,0]
	v_pk_mul_f32 v[50:51], v[50:51], v[88:89] op_sel_hi:[1,0]
	v_pk_mul_f32 v[28:29], v[28:29], v[186:187] op_sel_hi:[1,0]
	v_pk_mul_f32 v[30:31], v[30:31], v[186:187] op_sel_hi:[1,0]
	v_pk_mul_f32 v[24:25], v[24:25], v[186:187] op_sel_hi:[1,0]
	v_pk_mul_f32 v[26:27], v[26:27], v[186:187] op_sel_hi:[1,0]
	v_pk_mul_f32 v[20:21], v[20:21], v[186:187] op_sel_hi:[1,0]
	v_pk_mul_f32 v[22:23], v[22:23], v[186:187] op_sel_hi:[1,0]
	v_pk_mul_f32 v[16:17], v[16:17], v[186:187] op_sel_hi:[1,0]
	v_pk_mul_f32 v[18:19], v[18:19], v[186:187] op_sel_hi:[1,0]
.Lpast_noresc:
	v_exp_f32_e32 v68, v68
	v_exp_f32_e32 v69, v69
	v_exp_f32_e32 v70, v70
	v_exp_f32_e32 v71, v71
	v_pk_add_f32 v[100:101], v[100:101], v[178:179] op_sel_hi:[1,0]
	v_pk_add_f32 v[102:103], v[102:103], v[178:179] op_sel_hi:[1,0]
	v_exp_f32_e32 v72, v72
	v_exp_f32_e32 v73, v73
	v_exp_f32_e32 v74, v74
	v_exp_f32_e32 v75, v75
	v_exp_f32_e32 v64, v64
	v_exp_f32_e32 v65, v65
	v_exp_f32_e32 v66, v66
	v_exp_f32_e32 v67, v67
	v_exp_f32_e32 v100, v100
	v_exp_f32_e32 v101, v101
	v_exp_f32_e32 v102, v102
	v_exp_f32_e32 v103, v103
	v_cvt_pk_bf16_f32 v222, v68, v69
	v_cvt_pk_bf16_f32 v223, v70, v71
	v_cvt_pk_bf16_f32 v224, v64, v65
	v_cvt_pk_bf16_f32 v225, v66, v67
	s_waitcnt lgkmcnt(7)
	v_mfma_f32_16x16x32_bf16 v[60:63], v[104:107], v[222:225], v[60:63]
	v_cvt_pk_bf16_f32 v226, v72, v73
	v_cvt_pk_bf16_f32 v227, v74, v75
	s_waitcnt lgkmcnt(5)
	v_mfma_f32_16x16x32_bf16 v[56:59], v[84:87], v[222:225], v[56:59]
	v_cvt_pk_bf16_f32 v228, v100, v101
	v_cvt_pk_bf16_f32 v229, v102, v103
	s_nop 1
	v_mfma_f32_16x16x32_bf16 v[28:31], v[104:107], v[226:229], v[28:31]
	v_add_f32_e32 v92, v92, v90
	v_add_f32_e32 v93, v93, v90
	v_add_f32_e32 v94, v94, v90
	v_add_f32_e32 v95, v95, v90
	v_mfma_f32_16x16x32_bf16 v[24:27], v[84:87], v[226:229], v[24:27]
	v_add_f32_e32 v96, v96, v90
	v_add_f32_e32 v97, v97, v90
	v_add_f32_e32 v98, v98, v90
	v_add_f32_e32 v99, v99, v90
	s_waitcnt lgkmcnt(3)
	v_mfma_f32_16x16x32_bf16 v[52:55], v[206:209], v[222:225], v[52:55]
	v_exp_f32_e32 v92, v92
	v_exp_f32_e32 v93, v93
	v_exp_f32_e32 v94, v94
	v_exp_f32_e32 v95, v95
	s_waitcnt lgkmcnt(1)
	v_mfma_f32_16x16x32_bf16 v[48:51], v[214:217], v[222:225], v[48:51]
	v_exp_f32_e32 v96, v96
	v_exp_f32_e32 v97, v97
	v_exp_f32_e32 v98, v98
	v_exp_f32_e32 v99, v99
	v_add_f32_e32 v76, v76, v178
	v_add_f32_e32 v77, v77, v178
	v_add_f32_e32 v78, v78, v178
	v_add_f32_e32 v79, v79, v178
	v_add_f32_e32 v80, v80, v178
	v_add_f32_e32 v81, v81, v178
	v_add_f32_e32 v82, v82, v178
	v_add_f32_e32 v83, v83, v178
	v_cvt_pk_bf16_f32 v222, v92, v93
	v_cvt_pk_bf16_f32 v223, v94, v95
	v_cvt_pk_bf16_f32 v224, v96, v97
	v_cvt_pk_bf16_f32 v225, v98, v99
	v_exp_f32_e32 v76, v76
	v_exp_f32_e32 v77, v77
	s_nop 1
	v_mfma_f32_16x16x32_bf16 v[60:63], v[198:201], v[222:225], v[60:63]
	v_exp_f32_e32 v78, v78
	v_exp_f32_e32 v79, v79
	v_mfma_f32_16x16x32_bf16 v[56:59], v[202:205], v[222:225], v[56:59]
	v_exp_f32_e32 v80, v80
	v_exp_f32_e32 v81, v81
	v_mfma_f32_16x16x32_bf16 v[52:55], v[210:213], v[222:225], v[52:55]
	v_exp_f32_e32 v82, v82
	v_exp_f32_e32 v83, v83
	s_waitcnt lgkmcnt(0)
	v_mfma_f32_16x16x32_bf16 v[48:51], v[218:221], v[222:225], v[48:51]
	ds_read_b128 v[234:237], v116 offset:2304
	ds_read_b128 v[238:241], v116
	s_nop 1
	v_mfma_f32_16x16x32_bf16 v[20:23], v[206:209], v[226:229], v[20:23]
	v_add_f32_e32 v90, v68, v70
	v_add_f32_e32 v91, v69, v71
	v_add_f32_e32 v178, v72, v74
	v_add_f32_e32 v179, v73, v75
	v_mfma_f32_16x16x32_bf16 v[16:19], v[214:217], v[226:229], v[16:19]
	v_cvt_pk_bf16_f32 v226, v76, v77
	v_cvt_pk_bf16_f32 v227, v78, v79
	v_cvt_pk_bf16_f32 v228, v80, v81
	v_cvt_pk_bf16_f32 v229, v82, v83
	v_add_f32_e32 v90, v90, v64
	v_add_f32_e32 v91, v91, v65
	v_add_f32_e32 v178, v178, v100
	v_add_f32_e32 v179, v179, v101
	s_nop 1
	v_mfma_f32_16x16x32_bf16 v[28:31], v[198:201], v[226:229], v[28:31]
	v_add_f32_e32 v90, v90, v66
	v_add_f32_e32 v91, v91, v67
	v_add_f32_e32 v178, v178, v102
	v_add_f32_e32 v179, v179, v103
	v_mfma_f32_16x16x32_bf16 v[24:27], v[202:205], v[226:229], v[24:27]
	v_add_f32_e32 v90, v90, v92
	v_add_f32_e32 v91, v91, v93
	v_add_f32_e32 v178, v178, v76
	v_add_f32_e32 v179, v179, v77
	v_mfma_f32_16x16x32_bf16 v[20:23], v[210:213], v[226:229], v[20:23]
	v_add_f32_e32 v90, v90, v94
	v_add_f32_e32 v91, v91, v95
	v_add_f32_e32 v178, v178, v78
	v_add_f32_e32 v179, v179, v79
	v_mfma_f32_16x16x32_bf16 v[16:19], v[218:221], v[226:229], v[16:19]
	v_add_f32_e32 v90, v90, v96
	v_add_f32_e32 v91, v91, v97
	v_add_f32_e32 v178, v178, v80
	v_add_f32_e32 v179, v179, v81
	v_add_f32_e32 v90, v90, v98
	v_add_f32_e32 v91, v91, v99
	v_add_f32_e32 v178, v178, v82
	v_add_f32_e32 v179, v179, v83
	v_add_f32_e32 v64, v90, v91
	v_add_f32_e32 v65, v178, v179
	v_fma_f32 v158, v158, v88, v64
	v_fma_f32 v159, v159, v89, v65
	s_cmpk_lg_i32 s0, 0x80
	s_cbranch_scc1 .Lpast_qskip
	s_cmp_lg_u64 s[22:23], 0
	s_cbranch_scc1 .Lpast_qskip
	v_mov_b32_e32 v233, 0
	s_waitcnt vmcnt(1)
	v_and_b32_e32 v137, 0xfff, v141
	v_lshlrev_b32_e32 v232, 7, v137
	v_lshl_add_u64 v[4:5], v[156:157], 0, v[232:233]
	global_load_dwordx4 v[0:3], v[4:5], off
	s_nop 0
	global_load_dwordx4 v[4:7], v[4:5], off offset:64
	s_waitcnt vmcnt(2)
	v_and_b32_e32 v139, 0xfff, v149
	v_lshlrev_b32_e32 v232, 7, v139
	v_lshl_add_u64 v[12:13], v[156:157], 0, v[232:233]
	global_load_dwordx4 v[8:11], v[12:13], off
	s_nop 0
	global_load_dwordx4 v[12:15], v[12:13], off offset:64
